# q up-projection epilogue (P4) rewritten by hand: hoisted row-statistic loads, in-place packed scale, running store pointer
# baseline (speedup 1.0000x reference)
.LBB0_1088:
	s_and_b64 vcc, exec, s[0:1]
	s_cbranch_vccz .LBB0_1090
	s_waitcnt lgkmcnt(0)
	v_ashrrev_i32_e32 v82, 2, v192
	v_and_b32_e32 v80, 15, v192
	v_and_b32_e32 v82, 0xffffffc0, v82
	v_add3_u32 v134, v80, s30, v82
	v_ashrrev_i32_e32 v135, 31, v134
	v_lshl_add_u64 v[82:83], v[134:135], 2, s[90:91]
	s_mov_b64 vcc, 0x80000
	s_nop 0
	v_lshl_add_u64 v[82:83], v[82:83], 0, vcc
	global_load_dword v204, v[82:83], off
	global_load_dword v205, v[82:83], off offset:64
	global_load_dword v206, v[82:83], off offset:128
	global_load_dword v207, v[82:83], off offset:192
	global_load_dword v208, v[82:83], off offset:512
	global_load_dword v209, v[82:83], off offset:576
	global_load_dword v210, v[82:83], off offset:640
	global_load_dword v211, v[82:83], off offset:704
	v_readlane_b32 s0, v252, 24
	s_movk_i32 s37, 0x600
	v_readlane_b32 s1, v252, 25
	s_mov_b32 s16, 0x80000
	s_ashr_i32 s7, s6, 31
	v_mov_b64_e32 v[132:133], s[0:1]
	v_mad_i64_i32 v[136:137], s[0:1], v134, s37, v[132:133]
	s_lshl_b64 s[0:1], s[6:7], 1
	s_nop 0
	v_lshl_add_u64 v[136:137], v[136:137], 0, s[0:1]
	v_and_b32_e32 v80, 0xc0, v192
	v_lshl_add_u64 v[136:137], v[136:137], 0, v[80:81]
	v_and_b32_e32 v80, 48, v192
	v_lshl_add_u64 v[136:137], v[136:137], 0, v[80:81]
	s_mov_b32 s7, 0x80000
	s_waitcnt vmcnt(7)
	v_fmamk_f32 v244, v204, 0x3b2aaaab, v194
	v_rsq_f32_e32 v244, v244
	s_nop 0
	v_pk_mul_f32 v[128:129], v[128:129], v[244:245] op_sel_hi:[1,0]
	v_pk_mul_f32 v[130:131], v[130:131], v[244:245] op_sel_hi:[1,0]
	v_pk_mul_f32 v[124:125], v[124:125], v[244:245] op_sel_hi:[1,0]
	v_pk_mul_f32 v[126:127], v[126:127], v[244:245] op_sel_hi:[1,0]
	v_cvt_pk_bf16_f32 v128, v128, v129
	v_cvt_pk_bf16_f32 v129, v130, v131
	v_cvt_pk_bf16_f32 v130, v124, v125
	v_cvt_pk_bf16_f32 v131, v126, v127
	global_store_dwordx4 v[136:137], v[128:131], off
	v_pk_mul_f32 v[120:121], v[120:121], v[244:245] op_sel_hi:[1,0]
	v_pk_mul_f32 v[122:123], v[122:123], v[244:245] op_sel_hi:[1,0]
	v_pk_mul_f32 v[116:117], v[116:117], v[244:245] op_sel_hi:[1,0]
	v_pk_mul_f32 v[118:119], v[118:119], v[244:245] op_sel_hi:[1,0]
	v_cvt_pk_bf16_f32 v120, v120, v121
	v_cvt_pk_bf16_f32 v121, v122, v123
	v_cvt_pk_bf16_f32 v122, v116, v117
	v_cvt_pk_bf16_f32 v123, v118, v119
	global_store_dwordx4 v[136:137], v[120:123], off offset:256
	s_mov_b64 vcc, 0x6000
	s_nop 0
	v_lshl_add_u64 v[136:137], v[136:137], 0, vcc
	s_waitcnt vmcnt(8)
	v_fmamk_f32 v244, v205, 0x3b2aaaab, v194
	v_rsq_f32_e32 v244, v244
	s_nop 0
	v_pk_mul_f32 v[112:113], v[112:113], v[244:245] op_sel_hi:[1,0]
	v_pk_mul_f32 v[114:115], v[114:115], v[244:245] op_sel_hi:[1,0]
	v_pk_mul_f32 v[108:109], v[108:109], v[244:245] op_sel_hi:[1,0]
	v_pk_mul_f32 v[110:111], v[110:111], v[244:245] op_sel_hi:[1,0]
	v_cvt_pk_bf16_f32 v112, v112, v113
	v_cvt_pk_bf16_f32 v113, v114, v115
	v_cvt_pk_bf16_f32 v114, v108, v109
	v_cvt_pk_bf16_f32 v115, v110, v111
	global_store_dwordx4 v[136:137], v[112:115], off
	v_pk_mul_f32 v[104:105], v[104:105], v[244:245] op_sel_hi:[1,0]
	v_pk_mul_f32 v[106:107], v[106:107], v[244:245] op_sel_hi:[1,0]
	v_pk_mul_f32 v[100:101], v[100:101], v[244:245] op_sel_hi:[1,0]
	v_pk_mul_f32 v[102:103], v[102:103], v[244:245] op_sel_hi:[1,0]
	v_cvt_pk_bf16_f32 v104, v104, v105
	v_cvt_pk_bf16_f32 v105, v106, v107
	v_cvt_pk_bf16_f32 v106, v100, v101
	v_cvt_pk_bf16_f32 v107, v102, v103
	global_store_dwordx4 v[136:137], v[104:107], off offset:256
	s_mov_b64 vcc, 0x6000
	s_nop 0
	v_lshl_add_u64 v[136:137], v[136:137], 0, vcc
	s_waitcnt vmcnt(9)
	v_fmamk_f32 v244, v206, 0x3b2aaaab, v194
	v_rsq_f32_e32 v244, v244
	s_nop 0
	v_pk_mul_f32 v[96:97], v[96:97], v[244:245] op_sel_hi:[1,0]
	v_pk_mul_f32 v[98:99], v[98:99], v[244:245] op_sel_hi:[1,0]
	v_pk_mul_f32 v[92:93], v[92:93], v[244:245] op_sel_hi:[1,0]
	v_pk_mul_f32 v[94:95], v[94:95], v[244:245] op_sel_hi:[1,0]
	v_cvt_pk_bf16_f32 v96, v96, v97
	v_cvt_pk_bf16_f32 v97, v98, v99
	v_cvt_pk_bf16_f32 v98, v92, v93
	v_cvt_pk_bf16_f32 v99, v94, v95
	global_store_dwordx4 v[136:137], v[96:99], off
	v_pk_mul_f32 v[88:89], v[88:89], v[244:245] op_sel_hi:[1,0]
	v_pk_mul_f32 v[90:91], v[90:91], v[244:245] op_sel_hi:[1,0]
	v_pk_mul_f32 v[84:85], v[84:85], v[244:245] op_sel_hi:[1,0]
	v_pk_mul_f32 v[86:87], v[86:87], v[244:245] op_sel_hi:[1,0]
	v_cvt_pk_bf16_f32 v88, v88, v89
	v_cvt_pk_bf16_f32 v89, v90, v91
	v_cvt_pk_bf16_f32 v90, v84, v85
	v_cvt_pk_bf16_f32 v91, v86, v87
	global_store_dwordx4 v[136:137], v[88:91], off offset:256
	s_mov_b64 vcc, 0x6000
	s_nop 0
	v_lshl_add_u64 v[136:137], v[136:137], 0, vcc
	s_waitcnt vmcnt(10)
	v_fmamk_f32 v244, v207, 0x3b2aaaab, v194
	v_rsq_f32_e32 v244, v244
	s_nop 0
	v_pk_mul_f32 v[76:77], v[76:77], v[244:245] op_sel_hi:[1,0]
	v_pk_mul_f32 v[78:79], v[78:79], v[244:245] op_sel_hi:[1,0]
	v_pk_mul_f32 v[72:73], v[72:73], v[244:245] op_sel_hi:[1,0]
	v_pk_mul_f32 v[74:75], v[74:75], v[244:245] op_sel_hi:[1,0]
	v_cvt_pk_bf16_f32 v76, v76, v77
	v_cvt_pk_bf16_f32 v77, v78, v79
	v_cvt_pk_bf16_f32 v78, v72, v73
	v_cvt_pk_bf16_f32 v79, v74, v75
	global_store_dwordx4 v[136:137], v[76:79], off
	v_pk_mul_f32 v[68:69], v[68:69], v[244:245] op_sel_hi:[1,0]
	v_pk_mul_f32 v[70:71], v[70:71], v[244:245] op_sel_hi:[1,0]
	v_pk_mul_f32 v[64:65], v[64:65], v[244:245] op_sel_hi:[1,0]
	v_pk_mul_f32 v[66:67], v[66:67], v[244:245] op_sel_hi:[1,0]
	v_cvt_pk_bf16_f32 v68, v68, v69
	v_cvt_pk_bf16_f32 v69, v70, v71
	v_cvt_pk_bf16_f32 v70, v64, v65
	v_cvt_pk_bf16_f32 v71, v66, v67
	global_store_dwordx4 v[136:137], v[68:71], off offset:256
	s_mov_b64 vcc, 0x1e000
	s_nop 0
	v_lshl_add_u64 v[136:137], v[136:137], 0, vcc
	s_waitcnt vmcnt(11)
	v_fmamk_f32 v244, v208, 0x3b2aaaab, v194
	v_rsq_f32_e32 v244, v244
	s_nop 0
	v_pk_mul_f32 v[60:61], v[60:61], v[244:245] op_sel_hi:[1,0]
	v_pk_mul_f32 v[62:63], v[62:63], v[244:245] op_sel_hi:[1,0]
	v_pk_mul_f32 v[56:57], v[56:57], v[244:245] op_sel_hi:[1,0]
	v_pk_mul_f32 v[58:59], v[58:59], v[244:245] op_sel_hi:[1,0]
	v_cvt_pk_bf16_f32 v60, v60, v61
	v_cvt_pk_bf16_f32 v61, v62, v63
	v_cvt_pk_bf16_f32 v62, v56, v57
	v_cvt_pk_bf16_f32 v63, v58, v59
	global_store_dwordx4 v[136:137], v[60:63], off
	v_pk_mul_f32 v[52:53], v[52:53], v[244:245] op_sel_hi:[1,0]
	v_pk_mul_f32 v[54:55], v[54:55], v[244:245] op_sel_hi:[1,0]
	v_pk_mul_f32 v[48:49], v[48:49], v[244:245] op_sel_hi:[1,0]
	v_pk_mul_f32 v[50:51], v[50:51], v[244:245] op_sel_hi:[1,0]
	v_cvt_pk_bf16_f32 v52, v52, v53
	v_cvt_pk_bf16_f32 v53, v54, v55
	v_cvt_pk_bf16_f32 v54, v48, v49
	v_cvt_pk_bf16_f32 v55, v50, v51
	global_store_dwordx4 v[136:137], v[52:55], off offset:256
	s_mov_b64 vcc, 0x6000
	s_nop 0
	v_lshl_add_u64 v[136:137], v[136:137], 0, vcc
	s_waitcnt vmcnt(12)
	v_fmamk_f32 v244, v209, 0x3b2aaaab, v194
	v_rsq_f32_e32 v244, v244
	s_nop 0
	v_pk_mul_f32 v[44:45], v[44:45], v[244:245] op_sel_hi:[1,0]
	v_pk_mul_f32 v[46:47], v[46:47], v[244:245] op_sel_hi:[1,0]
	v_pk_mul_f32 v[40:41], v[40:41], v[244:245] op_sel_hi:[1,0]
	v_pk_mul_f32 v[42:43], v[42:43], v[244:245] op_sel_hi:[1,0]
	v_cvt_pk_bf16_f32 v44, v44, v45
	v_cvt_pk_bf16_f32 v45, v46, v47
	v_cvt_pk_bf16_f32 v46, v40, v41
	v_cvt_pk_bf16_f32 v47, v42, v43
	global_store_dwordx4 v[136:137], v[44:47], off
	v_pk_mul_f32 v[36:37], v[36:37], v[244:245] op_sel_hi:[1,0]
	v_pk_mul_f32 v[38:39], v[38:39], v[244:245] op_sel_hi:[1,0]
	v_pk_mul_f32 v[32:33], v[32:33], v[244:245] op_sel_hi:[1,0]
	v_pk_mul_f32 v[34:35], v[34:35], v[244:245] op_sel_hi:[1,0]
	v_cvt_pk_bf16_f32 v36, v36, v37
	v_cvt_pk_bf16_f32 v37, v38, v39
	v_cvt_pk_bf16_f32 v38, v32, v33
	v_cvt_pk_bf16_f32 v39, v34, v35
	global_store_dwordx4 v[136:137], v[36:39], off offset:256
	s_mov_b64 vcc, 0x6000
	s_nop 0
	v_lshl_add_u64 v[136:137], v[136:137], 0, vcc
	s_waitcnt vmcnt(13)
	v_fmamk_f32 v244, v210, 0x3b2aaaab, v194
	v_rsq_f32_e32 v244, v244
	s_nop 0
	v_pk_mul_f32 v[28:29], v[28:29], v[244:245] op_sel_hi:[1,0]
	v_pk_mul_f32 v[30:31], v[30:31], v[244:245] op_sel_hi:[1,0]
	v_pk_mul_f32 v[24:25], v[24:25], v[244:245] op_sel_hi:[1,0]
	v_pk_mul_f32 v[26:27], v[26:27], v[244:245] op_sel_hi:[1,0]
	v_cvt_pk_bf16_f32 v28, v28, v29
	v_cvt_pk_bf16_f32 v29, v30, v31
	v_cvt_pk_bf16_f32 v30, v24, v25
	v_cvt_pk_bf16_f32 v31, v26, v27
	global_store_dwordx4 v[136:137], v[28:31], off
	v_pk_mul_f32 v[20:21], v[20:21], v[244:245] op_sel_hi:[1,0]
	v_pk_mul_f32 v[22:23], v[22:23], v[244:245] op_sel_hi:[1,0]
	v_pk_mul_f32 v[16:17], v[16:17], v[244:245] op_sel_hi:[1,0]
	v_pk_mul_f32 v[18:19], v[18:19], v[244:245] op_sel_hi:[1,0]
	v_cvt_pk_bf16_f32 v20, v20, v21
	v_cvt_pk_bf16_f32 v21, v22, v23
	v_cvt_pk_bf16_f32 v22, v16, v17
	v_cvt_pk_bf16_f32 v23, v18, v19
	global_store_dwordx4 v[136:137], v[20:23], off offset:256
	s_mov_b64 vcc, 0x6000
	s_nop 0
	v_lshl_add_u64 v[136:137], v[136:137], 0, vcc
	s_waitcnt vmcnt(14)
	v_fmamk_f32 v244, v211, 0x3b2aaaab, v194
	v_rsq_f32_e32 v244, v244
	s_nop 0
	v_pk_mul_f32 v[12:13], v[12:13], v[244:245] op_sel_hi:[1,0]
	v_pk_mul_f32 v[14:15], v[14:15], v[244:245] op_sel_hi:[1,0]
	v_pk_mul_f32 v[8:9], v[8:9], v[244:245] op_sel_hi:[1,0]
	v_pk_mul_f32 v[10:11], v[10:11], v[244:245] op_sel_hi:[1,0]
	v_cvt_pk_bf16_f32 v12, v12, v13
	v_cvt_pk_bf16_f32 v13, v14, v15
	v_cvt_pk_bf16_f32 v14, v8, v9
	v_cvt_pk_bf16_f32 v15, v10, v11
	global_store_dwordx4 v[136:137], v[12:15], off
	v_pk_mul_f32 v[4:5], v[4:5], v[244:245] op_sel_hi:[1,0]
	v_pk_mul_f32 v[6:7], v[6:7], v[244:245] op_sel_hi:[1,0]
	v_pk_mul_f32 v[0:1], v[0:1], v[244:245] op_sel_hi:[1,0]
	v_pk_mul_f32 v[2:3], v[2:3], v[244:245] op_sel_hi:[1,0]
	v_cvt_pk_bf16_f32 v4, v4, v5
	v_cvt_pk_bf16_f32 v5, v6, v7
	v_cvt_pk_bf16_f32 v6, v0, v1
	v_cvt_pk_bf16_f32 v7, v2, v3
	global_store_dwordx4 v[136:137], v[4:7], off offset:256
